# baseline (speedup 1.0000x reference)
; __device__ __forceinline__ int bidx() { int t = blockIdx.x; asm volatile("" : "+s"(t)); return t; }
; __device__ __forceinline__ void xatt_phase(const P& p_, int layer, char* smem, bool dry = false) {
;     ...
;   for (int item = bidx(); item < 1024; item += gridDim.x) {
;     const int b = item >> 8, h = (item >> 6) & 3, qt = (item >> 1) & 31, eh = item & 1;
;     const int tok = b * S_ + qt * 128 + qslot;
;     h8 qf[16];
; #pragma unroll
;     for (int dd = 0; dd < 16; ++dd) qf[dd] = *(const h8*)(Qx + (size_t)tok * 1024 + h * 256 + dd * 16 + hi * 8) * (h16)0.0625f;
.LBB0_1280:
	s_bfe_u32 s0, s47, 0x20008
	s_lshl_b32 s1, s48, 11
	s_and_b32 s1, s1, 0x40000
	s_lshl_b32 s2, s0, 19
	s_or_b32 s53, s2, s1
	s_lshl_b32 s33, s0, 9
	s_lshl_b32 s0, s17, 4
	s_lshl_b32 s1, s17, 6
	s_and_b32 s0, s0, 0xfffff000
	s_and_b32 s1, s1, 0xf80
	s_or_b32 s0, s0, s1
	v_add_u32_e32 v2, s0, v231
	v_ashrrev_i32_e32 v3, 31, v2
	s_lshl_b32 s0, s17, 2
	v_lshlrev_b64 v[186:187], 11, v[2:3]
	s_and_b32 s52, s0, 0x300
	v_lshl_add_u64 v[2:3], s[6:7], 0, v[186:187]
	s_lshl_b32 s88, s52, 1
	v_lshl_add_u64 v[2:3], v[2:3], 0, s[88:89]
	v_mov_b32_e32 v183, v1
	v_lshl_add_u64 v[6:7], v[2:3], 0, v[182:183]
	global_load_dwordx4 v[112:115], v[6:7], off
	global_load_dwordx4 v[116:119], v[6:7], off offset:32
	global_load_dwordx4 v[120:123], v[6:7], off offset:64
	global_load_dwordx4 v[124:127], v[6:7], off offset:96
	global_load_dwordx4 v[128:131], v[6:7], off offset:128
	global_load_dwordx4 v[132:135], v[6:7], off offset:160
	global_load_dwordx4 v[136:139], v[6:7], off offset:192
	global_load_dwordx4 v[140:143], v[6:7], off offset:224
	global_load_dwordx4 v[144:147], v[6:7], off offset:256
	global_load_dwordx4 v[148:151], v[6:7], off offset:288
	global_load_dwordx4 v[152:155], v[6:7], off offset:320
	global_load_dwordx4 v[156:159], v[6:7], off offset:352
	global_load_dwordx4 v[160:163], v[6:7], off offset:384
	global_load_dwordx4 v[164:167], v[6:7], off offset:416
	global_load_dwordx4 v[168:171], v[6:7], off offset:448
	global_load_dwordx4 v[2:5], v[6:7], off offset:480
	s_movk_i32 s0, 0x2c00
	v_mov_b32_e32 v70, v180
	s_movk_i32 s3, 0x90
	s_mov_b32 s49, 4
	s_waitcnt vmcnt(1)
	v_pk_mul_f16 v115, v115, s0 op_sel_hi:[1,0]
	v_pk_mul_f16 v114, v114, s0 op_sel_hi:[1,0]
	v_pk_mul_f16 v113, v113, s0 op_sel_hi:[1,0]
	v_pk_mul_f16 v112, v112, s0 op_sel_hi:[1,0]
	v_pk_mul_f16 v119, v119, s0 op_sel_hi:[1,0]
	v_pk_mul_f16 v118, v118, s0 op_sel_hi:[1,0]
	v_pk_mul_f16 v117, v117, s0 op_sel_hi:[1,0]
	v_pk_mul_f16 v116, v116, s0 op_sel_hi:[1,0]
	v_pk_mul_f16 v123, v123, s0 op_sel_hi:[1,0]
	v_pk_mul_f16 v122, v122, s0 op_sel_hi:[1,0]
	v_pk_mul_f16 v121, v121, s0 op_sel_hi:[1,0]
	v_pk_mul_f16 v120, v120, s0 op_sel_hi:[1,0]
	v_pk_mul_f16 v127, v127, s0 op_sel_hi:[1,0]
	v_pk_mul_f16 v126, v126, s0 op_sel_hi:[1,0]
	v_pk_mul_f16 v125, v125, s0 op_sel_hi:[1,0]
	v_pk_mul_f16 v124, v124, s0 op_sel_hi:[1,0]
	v_pk_mul_f16 v131, v131, s0 op_sel_hi:[1,0]
	v_pk_mul_f16 v130, v130, s0 op_sel_hi:[1,0]
	v_pk_mul_f16 v129, v129, s0 op_sel_hi:[1,0]
	v_pk_mul_f16 v128, v128, s0 op_sel_hi:[1,0]
	v_pk_mul_f16 v135, v135, s0 op_sel_hi:[1,0]
	v_pk_mul_f16 v134, v134, s0 op_sel_hi:[1,0]
	v_pk_mul_f16 v133, v133, s0 op_sel_hi:[1,0]
	v_pk_mul_f16 v132, v132, s0 op_sel_hi:[1,0]
	v_pk_mul_f16 v139, v139, s0 op_sel_hi:[1,0]
	v_pk_mul_f16 v138, v138, s0 op_sel_hi:[1,0]
	v_pk_mul_f16 v137, v137, s0 op_sel_hi:[1,0]
	v_pk_mul_f16 v136, v136, s0 op_sel_hi:[1,0]
	v_pk_mul_f16 v143, v143, s0 op_sel_hi:[1,0]
	v_pk_mul_f16 v142, v142, s0 op_sel_hi:[1,0]
	v_pk_mul_f16 v141, v141, s0 op_sel_hi:[1,0]
	v_pk_mul_f16 v140, v140, s0 op_sel_hi:[1,0]
	v_pk_mul_f16 v147, v147, s0 op_sel_hi:[1,0]
	v_pk_mul_f16 v146, v146, s0 op_sel_hi:[1,0]
	v_pk_mul_f16 v145, v145, s0 op_sel_hi:[1,0]
	v_pk_mul_f16 v144, v144, s0 op_sel_hi:[1,0]
	v_pk_mul_f16 v151, v151, s0 op_sel_hi:[1,0]
	v_pk_mul_f16 v150, v150, s0 op_sel_hi:[1,0]
	v_pk_mul_f16 v149, v149, s0 op_sel_hi:[1,0]
	v_pk_mul_f16 v148, v148, s0 op_sel_hi:[1,0]
	v_pk_mul_f16 v155, v155, s0 op_sel_hi:[1,0]
	v_pk_mul_f16 v154, v154, s0 op_sel_hi:[1,0]
	v_pk_mul_f16 v153, v153, s0 op_sel_hi:[1,0]
	v_pk_mul_f16 v152, v152, s0 op_sel_hi:[1,0]
	v_pk_mul_f16 v159, v159, s0 op_sel_hi:[1,0]
	v_pk_mul_f16 v158, v158, s0 op_sel_hi:[1,0]
	v_pk_mul_f16 v157, v157, s0 op_sel_hi:[1,0]
	v_pk_mul_f16 v156, v156, s0 op_sel_hi:[1,0]
	v_pk_mul_f16 v163, v163, s0 op_sel_hi:[1,0]
	v_pk_mul_f16 v162, v162, s0 op_sel_hi:[1,0]
	v_pk_mul_f16 v161, v161, s0 op_sel_hi:[1,0]
	v_pk_mul_f16 v160, v160, s0 op_sel_hi:[1,0]
	v_pk_mul_f16 v167, v167, s0 op_sel_hi:[1,0]
	v_pk_mul_f16 v166, v166, s0 op_sel_hi:[1,0]
	v_pk_mul_f16 v165, v165, s0 op_sel_hi:[1,0]
	v_pk_mul_f16 v164, v164, s0 op_sel_hi:[1,0]
	v_pk_mul_f16 v171, v171, s0 op_sel_hi:[1,0]
	v_pk_mul_f16 v170, v170, s0 op_sel_hi:[1,0]
	v_pk_mul_f16 v169, v169, s0 op_sel_hi:[1,0]
	v_pk_mul_f16 v168, v168, s0 op_sel_hi:[1,0]
	s_nop 0
	v_ashrrev_i32_e32 v0, 31, v70
	v_lshrrev_b32_e32 v0, 27, v0
	v_add_u32_e32 v0, v70, v0
	v_ashrrev_i32_e32 v24, 5, v0
	v_ashrrev_i32_e32 v25, 31, v24
	v_lshlrev_b32_e32 v0, 8, v24
	v_lshlrev_b64 v[22:23], 11, v[24:25]
	v_add_u32_e32 v25, 0x100, v70
	v_lshlrev_b32_e32 v6, 3, v25
	s_barrier
; template <int EQK, int EV, bool PF, class KP, class SC>
; __device__ __forceinline__ void flash_core(f16v (&o)[EV / 32], float& m_run, float& l_run, const h8 (&qf)[EQK / 16],
;                                            int kt0, int kt1, const KP& kp, const SC& sc, char* smem) {
;     ...
;   auto gload = [&](int kt) {
; #pragma unroll
;     for (int i = 0; i < NKC; ++i) { int c = tid + 256 * i, row = c / KCH, kc = (c - row * KCH) * 8; rk[i] = *(const h8*)(kp.kptr(kt, row) + kc); }
; #pragma unroll
;     for (int i = 0; i < NVC; ++i) { int c = tid + 256 * i, e = c >> 3, kc = (c & 7) * 8; rv[i] = *(const h8*)(kp.vptr(kt, e) + kc); }
;   };
; __device__ __forceinline__ void xatt_phase(const P& p_, int layer, char* smem, bool dry = false) {
;     ...
;     for (int dd = 0; dd < 16; ++dd) qf[dd] = *(const h8*)(Qx + (size_t)tok * 1024 + h * 256 + dd * 16 + hi * 8) * (h16)0.0625f;
	v_ashrrev_i32_e32 v188, 3, v70
	v_ashrrev_i32_e32 v190, 3, v25
	v_ashrrev_i32_e32 v189, 31, v188
	v_ashrrev_i32_e32 v191, 31, v190
	v_lshlrev_b64 v[202:203], 11, v[188:189]
	v_lshlrev_b64 v[200:201], 11, v[190:191]
	v_mul_lo_u32 v24, v24, s61
	v_and_b32_e32 v71, 31, v70
	s_waitcnt vmcnt(0)
	v_pk_mul_f16 v172, v2, s0 op_sel_hi:[1,0]
	v_lshlrev_b32_e32 v2, 3, v70
	v_sub_u32_e32 v28, v2, v0
	v_ashrrev_i32_e32 v0, 31, v25
	v_lshrrev_b32_e32 v0, 27, v0
	v_pk_mul_f16 v175, v5, s0 op_sel_hi:[1,0]
	v_pk_mul_f16 v174, v4, s0 op_sel_hi:[1,0]
	v_pk_mul_f16 v173, v3, s0 op_sel_hi:[1,0]
	s_and_b32 s0, s17, 0xffffff00
	v_add_u32_e32 v0, v25, v0
	s_ashr_i32 s1, s0, 31
	v_ashrrev_i32_e32 v29, 31, v28
	v_ashrrev_i32_e32 v46, 5, v0
	s_lshl_b64 s[12:13], s[0:1], 11
	v_lshlrev_b64 v[26:27], 1, v[28:29]
	v_lshlrev_b32_e32 v0, 8, v46
	v_add_u32_e32 v29, 0x200, v70
	s_add_u32 s2, s27, s12
	v_sub_u32_e32 v48, v6, v0
	v_ashrrev_i32_e32 v0, 31, v29
	s_addc_u32 s14, s36, s13
	v_lshrrev_b32_e32 v0, 27, v0
	s_add_u32 s24, s2, s88
	v_add_u32_e32 v0, v29, v0
	s_addc_u32 s25, s14, 0
	v_ashrrev_i32_e32 v47, 31, v46
	v_ashrrev_i32_e32 v52, 5, v0
	v_lshl_add_u64 v[2:3], s[24:25], 0, v[22:23]
	v_lshlrev_b64 v[30:31], 11, v[46:47]
	v_lshlrev_b32_e32 v0, 8, v52
	v_lshlrev_b32_e32 v10, 3, v29
	v_add_u32_e32 v47, 0x300, v70
	v_lshl_add_u64 v[2:3], v[2:3], 0, v[26:27]
	v_sub_u32_e32 v56, v10, v0
	v_ashrrev_i32_e32 v0, 31, v47
	global_load_dwordx4 v[2:5], v[2:3], off
	v_lshrrev_b32_e32 v0, 27, v0
	v_add_u32_e32 v0, v47, v0
	v_ashrrev_i32_e32 v58, 5, v0
	v_lshlrev_b32_e32 v0, 8, v58
	v_lshlrev_b32_e32 v14, 3, v47
	v_ashrrev_i32_e32 v53, 31, v52
	v_sub_u32_e32 v60, v14, v0
	v_ashrrev_i32_e32 v59, 31, v58
	v_ashrrev_i32_e32 v49, 31, v48
	v_lshlrev_b64 v[34:35], 11, v[52:53]
	v_ashrrev_i32_e32 v57, 31, v56
	v_lshlrev_b64 v[38:39], 11, v[58:59]
	v_ashrrev_i32_e32 v61, 31, v60
	v_lshl_add_u64 v[6:7], s[24:25], 0, v[30:31]
	v_lshlrev_b64 v[32:33], 1, v[48:49]
	v_lshl_add_u64 v[10:11], s[24:25], 0, v[34:35]
	v_lshlrev_b64 v[36:37], 1, v[56:57]
	v_lshl_add_u64 v[14:15], s[24:25], 0, v[38:39]
	v_lshlrev_b64 v[40:41], 1, v[60:61]
	v_lshl_add_u64 v[6:7], v[6:7], 0, v[32:33]
	v_lshl_add_u64 v[10:11], v[10:11], 0, v[36:37]
	v_lshl_add_u64 v[14:15], v[14:15], 0, v[40:41]
	global_load_dwordx4 v[6:9], v[6:7], off
	v_add_u32_e32 v0, 0x400, v70
	global_load_dwordx4 v[10:13], v[10:11], off
	v_ashrrev_i32_e32 v18, 31, v0
	global_load_dwordx4 v[14:17], v[14:15], off
	v_lshrrev_b32_e32 v18, 27, v18
	v_add_u32_e32 v18, v0, v18
	v_ashrrev_i32_e32 v66, 5, v18
	v_lshlrev_b32_e32 v18, 8, v66
	v_lshlrev_b32_e32 v0, 3, v0
	v_sub_u32_e32 v68, v0, v18
	v_add_u32_e32 v0, 0x500, v70
	v_ashrrev_i32_e32 v49, 31, v0
	v_lshrrev_b32_e32 v49, 27, v49
	v_add_u32_e32 v49, v0, v49
	v_ashrrev_i32_e32 v100, 5, v49
	v_lshlrev_b32_e32 v49, 8, v100
	v_lshlrev_b32_e32 v0, 3, v0
	v_sub_u32_e32 v102, v0, v49
	v_add_u32_e32 v0, 0x600, v70
	v_ashrrev_i32_e32 v49, 31, v0
	v_lshrrev_b32_e32 v49, 27, v49
	v_add_u32_e32 v49, v0, v49
	v_ashrrev_i32_e32 v104, 5, v49
	v_lshlrev_b32_e32 v49, 8, v104
	v_lshlrev_b32_e32 v0, 3, v0
	s_lshl_b32 s2, s17, 7
	v_sub_u32_e32 v106, v0, v49
	v_add_u32_e32 v0, 0x700, v70
	s_and_b32 s2, s2, 0x80
	v_ashrrev_i32_e32 v67, 31, v66
	v_ashrrev_i32_e32 v101, 31, v100
	v_ashrrev_i32_e32 v49, 31, v0
	s_or_b32 s14, s52, s2
	v_lshlrev_b64 v[42:43], 11, v[66:67]
	v_ashrrev_i32_e32 v69, 31, v68
	v_lshlrev_b64 v[50:51], 11, v[100:101]
	v_ashrrev_i32_e32 v103, 31, v102
	v_lshrrev_b32_e32 v49, 27, v49
	s_lshl_b32 s14, s14, 11
	v_lshl_add_u64 v[18:19], s[24:25], 0, v[42:43]
	v_lshlrev_b64 v[44:45], 1, v[68:69]
	v_lshl_add_u64 v[62:63], s[24:25], 0, v[50:51]
	v_lshlrev_b64 v[54:55], 1, v[102:103]
	v_add_u32_e32 v49, v0, v49
	s_add_u32 s22, s37, s14
	v_lshl_add_u64 v[18:19], v[18:19], 0, v[44:45]
	v_lshl_add_u64 v[62:63], v[62:63], 0, v[54:55]
	v_ashrrev_i32_e32 v105, 31, v104
	v_ashrrev_i32_e32 v108, 5, v49
	s_addc_u32 s56, s40, 0
	s_lshl_b64 s[14:15], s[0:1], 1
	global_load_dwordx4 v[18:21], v[18:19], off
	v_ashrrev_i32_e32 v107, 31, v106
	global_load_dwordx4 v[72:75], v[62:63], off
	v_lshlrev_b64 v[62:63], 11, v[104:105]
	v_lshlrev_b32_e32 v49, 8, v108
	v_lshlrev_b32_e32 v0, 3, v0
	v_ashrrev_i32_e32 v192, 3, v29
	v_ashrrev_i32_e32 v194, 3, v47
	s_add_u32 s0, s22, s14
	v_lshl_add_u64 v[76:77], s[24:25], 0, v[62:63]
	v_lshlrev_b64 v[64:65], 1, v[106:107]
	v_sub_u32_e32 v110, v0, v49
	v_ashrrev_i32_e32 v109, 31, v108
	v_ashrrev_i32_e32 v193, 31, v192
	v_ashrrev_i32_e32 v195, 31, v194
	s_addc_u32 s1, s56, s15
	v_lshl_add_u64 v[76:77], v[76:77], 0, v[64:65]
	v_lshlrev_b64 v[204:205], 11, v[108:109]
	v_ashrrev_i32_e32 v111, 31, v110
	v_lshlrev_b32_e32 v0, 4, v70
	v_lshlrev_b64 v[198:199], 11, v[192:193]
	v_lshlrev_b64 v[196:197], 11, v[194:195]
	global_load_dwordx4 v[76:79], v[76:77], off
	v_lshl_add_u64 v[80:81], s[24:25], 0, v[204:205]
	v_lshlrev_b64 v[206:207], 1, v[110:111]
	v_lshl_add_u64 v[84:85], s[0:1], 0, v[202:203]
	v_and_b32_e32 v0, 0x70, v0
	v_lshl_add_u64 v[88:89], s[0:1], 0, v[200:201]
	v_lshl_add_u64 v[92:93], s[0:1], 0, v[198:199]
	v_lshl_add_u64 v[96:97], s[0:1], 0, v[196:197]
	v_lshl_add_u64 v[80:81], v[80:81], 0, v[206:207]
	v_lshl_add_u64 v[84:85], v[84:85], 0, v[0:1]
	v_lshl_add_u64 v[88:89], v[88:89], 0, v[0:1]
	v_lshl_add_u64 v[92:93], v[92:93], 0, v[0:1]
	v_lshl_add_u64 v[96:97], v[96:97], 0, v[0:1]
	global_load_dwordx4 v[80:83], v[80:81], off
	v_lshl_add_u32 v183, v28, 1, v24
	global_load_dwordx4 v[84:87], v[84:85], off
	s_waitcnt vmcnt(8)
; template <int EQK, int EV, bool PF, class KP, class SC>
; __device__ __forceinline__ void flash_core(f16v (&o)[EV / 32], float& m_run, float& l_run, const h8 (&qf)[EQK / 16],
;                                            int kt0, int kt1, const KP& kp, const SC& sc, char* smem) {
;     ...
;   auto lstore = [&](int buf) {
;     h16* sK = base + buf * BUFH; h16* sV = sK + 64 * KLD;
; #pragma unroll
;     for (int i = 0; i < NKC; ++i) { int c = tid + 256 * i, row = c / KCH, kc = (c - row * KCH) * 8; *(h8*)(sK + row * KLD + kc) = rk[i]; }
; #pragma unroll
;     for (int i = 0; i < NVC; ++i) { int c = tid + 256 * i, e = c >> 3, kc = (c & 7) * 8; *(h8*)(sV + e * VLD + kc) = rv[i]; }
;   };
;   __syncthreads();
;   gload(kt0); lstore(0);
;   __syncthreads();
; __device__ __forceinline__ void xatt_phase(const P& p_, int layer, char* smem, bool dry = false) {
;     ...
;     f16v o[4];
; #pragma unroll
;     for (int et = 0; et < 4; ++et)
; #pragma unroll
;       for (int r = 0; r < 16; ++r) o[et][r] = 0.f;
;     float m_run = -1e30f, l_run = 0.f;
	ds_write_b128 v183, v[2:5]
	global_load_dwordx4 v[88:91], v[88:89], off
	v_mul_lo_u32 v2, v46, s61
	global_load_dwordx4 v[92:95], v[92:93], off
	v_lshl_add_u32 v185, v48, 1, v2
	global_load_dwordx4 v[96:99], v[96:97], off
	v_mul_lo_u32 v2, v52, s61
	v_lshl_add_u32 v232, v56, 1, v2
	v_mul_lo_u32 v2, v58, s61
	v_lshl_add_u32 v233, v60, 1, v2
	v_mul_lo_u32 v2, v66, s61
	v_lshl_add_u32 v234, v68, 1, v2
	v_mul_lo_u32 v2, v100, s61
	v_lshl_add_u32 v235, v102, 1, v2
	v_mul_lo_u32 v2, v104, s61
	v_lshl_add_u32 v236, v106, 1, v2
	v_mul_lo_u32 v2, v108, s61
	v_lshl_add_u32 v237, v110, 1, v2
	v_lshrrev_b32_e32 v2, 2, v70
	s_waitcnt vmcnt(10)
	ds_write_b128 v185, v[6:9]
	s_waitcnt vmcnt(9)
	ds_write_b128 v232, v[10:13]
	s_waitcnt vmcnt(8)
	ds_write_b128 v233, v[14:17]
	v_and_b32_e32 v16, 8, v2
	v_mad_u64_u32 v[188:189], s[0:1], v188, s3, v[0:1]
	v_lshlrev_b32_e32 v2, 1, v16
	v_mad_u32_u24 v189, v71, s61, v2
	v_lshl_add_u64 v[2:3], v[204:205], 0, s[12:13]
	v_or_b32_e32 v2, s33, v2
	v_lshl_add_u64 v[2:3], v[2:3], 0, v[206:207]
	v_lshl_add_u64 v[204:205], s[10:11], 0, v[2:3]
	v_lshl_add_u64 v[2:3], v[62:63], 0, s[12:13]
	v_or_b32_e32 v2, s33, v2
	v_lshl_add_u64 v[2:3], v[2:3], 0, v[64:65]
	v_lshl_add_u64 v[206:207], s[10:11], 0, v[2:3]
	v_lshl_add_u64 v[2:3], v[50:51], 0, s[12:13]
	v_or_b32_e32 v2, s33, v2
	v_lshl_add_u64 v[2:3], v[2:3], 0, v[54:55]
	v_lshl_add_u64 v[208:209], s[10:11], 0, v[2:3]
	v_lshl_add_u64 v[2:3], v[42:43], 0, s[12:13]
	v_or_b32_e32 v2, s33, v2
	v_lshl_add_u64 v[2:3], v[2:3], 0, v[44:45]
	v_lshl_add_u64 v[210:211], s[10:11], 0, v[2:3]
	v_lshl_add_u64 v[2:3], v[38:39], 0, s[12:13]
	v_or_b32_e32 v2, s33, v2
	v_lshl_add_u64 v[2:3], v[2:3], 0, v[40:41]
	v_lshl_add_u64 v[212:213], s[10:11], 0, v[2:3]
	v_lshl_add_u64 v[2:3], v[34:35], 0, s[12:13]
	v_or_b32_e32 v2, s33, v2
	v_lshl_add_u64 v[2:3], v[2:3], 0, v[36:37]
	v_lshl_add_u64 v[214:215], s[10:11], 0, v[2:3]
	v_lshl_add_u64 v[2:3], v[30:31], 0, s[12:13]
	v_or_b32_e32 v2, s33, v2
	v_mad_u64_u32 v[190:191], s[0:1], v190, s3, v[0:1]
	v_mad_u64_u32 v[192:193], s[0:1], v192, s3, v[0:1]
	v_mad_u64_u32 v[194:195], s[0:1], v194, s3, v[0:1]
	v_lshl_add_u64 v[2:3], v[2:3], 0, v[32:33]
	s_add_u32 s0, s41, s53
	v_lshl_add_u64 v[216:217], s[10:11], 0, v[2:3]
	v_lshl_add_u64 v[2:3], v[22:23], 0, s[12:13]
	s_addc_u32 s1, s46, 0
	v_or_b32_e32 v2, s33, v2
	v_mul_u32_u24_e32 v17, 0x90, v71
	s_add_u32 s0, s0, s14
	v_lshl_add_u64 v[2:3], v[2:3], 0, v[26:27]
	v_mov_b32_e32 v14, v1
	v_mov_b32_e32 v15, v1
	s_waitcnt vmcnt(7)
	ds_write_b128 v234, v[18:21]
	s_waitcnt vmcnt(6)
	ds_write_b128 v235, v[72:75]
	s_waitcnt vmcnt(5)
	ds_write_b128 v236, v[76:79]
	v_or_b32_e32 v196, v196, v0
	s_addc_u32 s1, s1, s15
	v_or_b32_e32 v198, v198, v0
	v_or_b32_e32 v200, v200, v0
	v_or_b32_e32 v202, v202, v0
	v_lshl_add_u64 v[218:219], s[10:11], 0, v[2:3]
	v_mov_b32_e32 v0, v1
	v_mov_b32_e32 v2, v1
	v_mov_b32_e32 v3, v1
	v_mov_b32_e32 v4, v1
	v_mov_b32_e32 v5, v1
	v_mov_b32_e32 v6, v1
	v_mov_b32_e32 v7, v1
	v_mov_b32_e32 v8, v1
	v_mov_b32_e32 v9, v1
	v_mov_b32_e32 v10, v1
	v_mov_b32_e32 v11, v1
	v_mov_b32_e32 v12, v1
	v_mov_b32_e32 v13, v1
	v_add_u32_e32 v193, v16, v17
	v_mov_b64_e32 v[30:31], v[14:15]
	v_mov_b64_e32 v[46:47], v[14:15]
	v_mov_b64_e32 v[62:63], v[14:15]
	v_mov_b64_e32 v[78:79], v[14:15]
	s_mov_b64 s[24:25], 0x20000
	v_lshl_add_u64 v[196:197], s[0:1], 0, v[196:197]
	v_lshl_add_u64 v[198:199], s[0:1], 0, v[198:199]
	v_lshl_add_u64 v[200:201], s[0:1], 0, v[200:201]
	v_lshl_add_u64 v[202:203], s[0:1], 0, v[202:203]
	v_mov_b32_e32 v191, 0xf149f2ca
	v_mov_b32_e32 v195, 0
	v_mov_b64_e32 v[28:29], v[12:13]
	v_mov_b64_e32 v[26:27], v[10:11]
	v_mov_b64_e32 v[24:25], v[8:9]
	v_mov_b64_e32 v[22:23], v[6:7]
	v_mov_b64_e32 v[20:21], v[4:5]
	v_mov_b64_e32 v[18:19], v[2:3]
	v_mov_b64_e32 v[16:17], v[0:1]
	v_mov_b64_e32 v[44:45], v[12:13]
	v_mov_b64_e32 v[42:43], v[10:11]
	v_mov_b64_e32 v[40:41], v[8:9]
	v_mov_b64_e32 v[38:39], v[6:7]
	v_mov_b64_e32 v[36:37], v[4:5]
	v_mov_b64_e32 v[34:35], v[2:3]
	v_mov_b64_e32 v[32:33], v[0:1]
	v_mov_b64_e32 v[60:61], v[12:13]
	v_mov_b64_e32 v[58:59], v[10:11]
	v_mov_b64_e32 v[56:57], v[8:9]
	v_mov_b64_e32 v[54:55], v[6:7]
	v_mov_b64_e32 v[52:53], v[4:5]
	v_mov_b64_e32 v[50:51], v[2:3]
	v_mov_b64_e32 v[48:49], v[0:1]
	v_mov_b64_e32 v[76:77], v[12:13]
	v_mov_b64_e32 v[74:75], v[10:11]
	v_mov_b64_e32 v[72:73], v[8:9]
	v_mov_b64_e32 v[70:71], v[6:7]
	v_mov_b64_e32 v[68:69], v[4:5]
	v_mov_b64_e32 v[66:67], v[2:3]
	v_mov_b64_e32 v[64:65], v[0:1]
	s_mov_b32 s0, 0xf149f2ca
	s_waitcnt vmcnt(4)
	ds_write_b128 v237, v[80:83]
	s_waitcnt vmcnt(3)
	ds_write_b128 v188, v[84:87] offset:33792
	s_waitcnt vmcnt(2)
	ds_write_b128 v190, v[88:91] offset:33792
	s_waitcnt vmcnt(1)
	ds_write_b128 v192, v[92:95] offset:33792
	s_waitcnt vmcnt(0)
	ds_write_b128 v194, v[96:99] offset:33792
	s_waitcnt lgkmcnt(0)
	s_barrier
